# phase 2: the 64 memory-KV projection tiles dealt as 128 half units to 128 CUs (template half-unit mode; EpiBf16X epilogue given roff / ai=0-only support), conv on the other 128 CUs
# speedup vs baseline: 1.0096x; 1.0036x over previous
.LBB0_21:
	s_or_b64 exec, exec, s[20:21]
	s_cmp_ge_i32 s74, s75
	s_cbranch_scc1 .LBB0_630
	s_add_u32 s22, s86, 0x4400000
	s_addc_u32 s23, s87, 0
	s_add_u32 s24, s86, 0x6400000
	s_addc_u32 s25, s87, 0
	s_add_u32 s26, s86, 0x8400000
	s_addc_u32 s27, s87, 0
	s_add_u32 s82, s86, 0xa400000
	s_addc_u32 s83, s87, 0
	s_add_u32 s4, s86, 0xc400000
	s_addc_u32 s5, s87, 0
	v_writelane_b32 v252, s4, 26
	v_mov_b32_e32 v97, 0
	v_mov_b32_e32 v225, 0x358637bd
	v_writelane_b32 v252, s5, 27
	s_add_u32 s4, s86, 0xd100000
	s_addc_u32 s5, s87, 0
	s_add_u32 s64, s86, 0xd200000
	v_writelane_b32 v252, s4, 28
	s_addc_u32 s65, s87, 0
	s_lshl_b32 s8, s14, 3
	s_lshl_b32 s34, s94, 3
	v_writelane_b32 v252, s5, 29
	s_add_u32 s4, s86, 0x3f00000
	s_addc_u32 s5, s87, 0
	v_writelane_b32 v252, s4, 30
	s_cmpk_lt_i32 s14, 0x200
	v_mov_b32_e32 v226, 1
	v_writelane_b32 v252, s5, 31
	s_cselect_b64 s[4:5], -1, 0
	v_writelane_b32 v252, s4, 32
	v_mov_b32_e32 v235, 0xff800000
	v_mov_b32_e32 v236, 0x7f800000
	v_writelane_b32 v252, s5, 33
	s_add_u32 s4, s86, 0x3900000
	s_addc_u32 s5, s87, 0
	v_writelane_b32 v252, s4, 34
	v_mov_b64_e32 v[196:197], 0x100
	v_mov_b32_e32 v237, 0xfffffd40
	v_writelane_b32 v252, s5, 35
	s_add_u32 s4, s86, 0x2e00000
	s_addc_u32 s5, s87, 0
	v_writelane_b32 v252, s4, 36
	v_mov_b32_e32 v238, 0xb00000
	v_mov_b32_e32 v239, 0x580000
	v_writelane_b32 v252, s5, 37
	s_add_u32 s4, s86, 0x1800000
	s_addc_u32 s5, s87, 0
	v_writelane_b32 v252, s4, 38
	v_mov_b32_e32 v240, 0xfffffa80
	v_mov_b32_e32 v241, 0x1600000
	v_writelane_b32 v252, s5, 39
	s_add_u32 s4, s86, 0x1400000
	s_addc_u32 s5, s87, 0
	s_add_u32 s9, s86, 0xc500000
	v_writelane_b32 v252, s4, 40
	s_addc_u32 s10, s87, 0
	s_ashr_i32 s70, s94, 31
	v_writelane_b32 v252, s5, 41
	s_add_u32 s4, s86, 0x800000
	s_addc_u32 s5, s87, 0
	v_writelane_b32 v252, s4, 42
	v_mov_b32_e32 v242, 0x1000
	v_mov_b32_e32 v243, 0x42800000
	v_writelane_b32 v252, s5, 43
	s_add_u32 s4, s86, 0x600000
	s_addc_u32 s5, s87, 0
	v_writelane_b32 v252, s4, 44
	s_cmp_lt_i32 s92, 0x80
	v_not_b32_e32 v244, 63
	v_writelane_b32 v252, s5, 45
	s_cselect_b64 s[4:5], -1, 0
	v_writelane_b32 v252, s4, 46
	s_mov_b32 s69, 0
	s_mov_b64 s[90:91], 0x80
	v_writelane_b32 v252, s5, 47
	s_ashr_i32 s4, s92, 6
	s_add_u32 s66, s86, 0xcd00000
	s_addc_u32 s67, s87, 0
	s_ashr_i32 s5, s4, 31
	s_lshl_b64 s[6:7], s[4:5], 21
	s_add_u32 s6, s66, s6
	s_addc_u32 s7, s67, s7
	v_writelane_b32 v252, s6, 48
	s_nop 1
	v_writelane_b32 v252, s7, 49
	s_add_u32 s6, s86, 0xc00000
	s_addc_u32 s7, s87, 0
	s_lshl_b64 s[4:5], s[4:5], 22
	s_add_u32 s12, s6, s4
	v_writelane_b32 v252, s6, 50
	s_addc_u32 s13, s7, s5
	s_nop 0
	v_writelane_b32 v252, s7, 51
	v_writelane_b32 v252, s12, 52
	s_and_b32 s6, s92, 63
	s_add_u32 s4, s9, s4
	v_writelane_b32 v252, s13, 53
	v_writelane_b32 v252, s6, 54
	v_writelane_b32 v252, s9, 55
	v_writelane_b32 v252, s10, 56
	s_addc_u32 s5, s10, s5
	v_writelane_b32 v252, s4, 57
	s_cmp_gt_i32 s92, 0x7f
	s_nop 0
	v_writelane_b32 v252, s5, 58
	s_cselect_b64 s[4:5], -1, 0
	v_writelane_b32 v252, s4, 59
	s_lshl_b32 s71, s94, 9
	s_add_i32 s72, s71, 0xffff0000
	v_writelane_b32 v252, s5, 60
	s_lshl_b32 s4, s92, 9
	s_add_i32 s4, s4, 0xffff0000
	v_writelane_b32 v252, s4, 61
	s_add_u32 s4, s42, 0x1000
	s_addc_u32 s5, s43, 0
	v_writelane_b32 v252, s4, 62
	s_nop 1
	v_writelane_b32 v252, s5, 63
	s_add_u32 s4, s86, 0x3d00000
	s_addc_u32 s5, s87, 0
	v_writelane_b32 v253, s4, 0
	s_nop 1
	v_writelane_b32 v253, s5, 1
	s_lshl_b32 s4, s14, 9
	v_writelane_b32 v253, s4, 2
	s_add_u32 s4, s86, 0xd400200
	s_addc_u32 s5, s87, 0
	s_add_u32 s10, s86, 0xd400400
	s_addc_u32 s11, s87, 0
	s_add_u32 s12, s86, 0xd400500
	s_addc_u32 s13, s87, 0
	s_add_u32 s16, s86, 0xd400600
	s_addc_u32 s17, s87, 0
	s_add_u32 s18, s86, 0xd400700
	s_addc_u32 s19, s87, 0
	s_add_u32 s52, s86, 0xd400800
	s_addc_u32 s53, s87, 0
	s_add_u32 s54, s86, 0xd400900
	s_addc_u32 s55, s87, 0
	s_add_u32 s56, s86, 0xd400a00
	s_addc_u32 s57, s87, 0
	s_add_u32 s58, s86, 0xd400b00
	s_addc_u32 s59, s87, 0
	s_add_u32 s60, s86, 0xd400c00
	s_addc_u32 s61, s87, 0
	s_add_u32 s62, s86, 0xd400d00
	s_addc_u32 s63, s87, 0
	s_add_u32 s76, s86, 0xd400e00
	s_addc_u32 s77, s87, 0
	s_add_u32 s78, s86, 0xd400f00
	v_writelane_b32 v253, s4, 3
	s_addc_u32 s79, s87, 0
	v_writelane_b32 v250, s58, 0
	v_writelane_b32 v253, s5, 4
	s_add_u32 s4, s86, 0xd401000
	s_addc_u32 s5, s87, 0
	s_add_u32 s6, s86, 0xd401100
	s_addc_u32 s7, s87, 0
	s_add_u32 s20, s86, 0xd401200
	s_addc_u32 s21, s87, 0
	s_add_u32 s28, s86, 0xd401300
	s_addc_u32 s29, s87, 0
	s_cmp_eq_u32 s3, 15
	s_cselect_b64 s[30:31], -1, 0
	v_writelane_b32 v253, s30, 5
	s_cmp_eq_u32 s3, 14
	v_writelane_b32 v250, s59, 1
	v_writelane_b32 v253, s31, 6
	s_cselect_b64 s[30:31], -1, 0
	v_writelane_b32 v253, s30, 7
	s_cmp_eq_u32 s3, 13
	v_writelane_b32 v250, s60, 2
	v_writelane_b32 v253, s31, 8
	s_cselect_b64 s[30:31], -1, 0
	v_writelane_b32 v253, s30, 9
	s_cmp_eq_u32 s3, 12
	v_writelane_b32 v250, s61, 3
	v_writelane_b32 v253, s31, 10
	s_cselect_b64 s[30:31], -1, 0
	v_writelane_b32 v253, s30, 11
	s_cmp_eq_u32 s3, 11
	v_writelane_b32 v250, s62, 4
	v_writelane_b32 v253, s31, 12
	s_cselect_b64 s[30:31], -1, 0
	v_writelane_b32 v253, s30, 13
	s_cmp_eq_u32 s3, 10
	v_writelane_b32 v250, s63, 5
	v_writelane_b32 v253, s31, 14
	s_cselect_b64 s[30:31], -1, 0
	v_writelane_b32 v253, s30, 15
	s_cmp_eq_u32 s3, 9
	v_writelane_b32 v250, s76, 6
	v_writelane_b32 v253, s31, 16
	s_cselect_b64 s[30:31], -1, 0
	v_writelane_b32 v253, s30, 17
	s_cmp_eq_u32 s3, 8
	v_writelane_b32 v250, s77, 7
	v_writelane_b32 v253, s31, 18
	s_cselect_b64 s[30:31], -1, 0
	v_writelane_b32 v253, s30, 19
	s_cmp_eq_u32 s3, 7
	v_writelane_b32 v250, s78, 8
	v_writelane_b32 v253, s31, 20
	s_cselect_b64 s[30:31], -1, 0
	v_writelane_b32 v253, s30, 21
	s_cmp_eq_u32 s3, 6
	v_writelane_b32 v250, s79, 9
	v_writelane_b32 v253, s31, 22
	s_cselect_b64 s[30:31], -1, 0
	v_writelane_b32 v253, s30, 23
	s_cmp_eq_u32 s3, 5
	s_nop 0
	v_writelane_b32 v253, s31, 24
	s_cselect_b64 s[30:31], -1, 0
	v_writelane_b32 v253, s30, 25
	s_cmp_eq_u32 s3, 4
	s_nop 0
	v_writelane_b32 v253, s31, 26
	s_cselect_b64 s[30:31], -1, 0
	v_writelane_b32 v253, s30, 27
	s_cmp_eq_u32 s3, 3
	s_nop 0
	v_writelane_b32 v253, s31, 28
	s_cselect_b64 s[30:31], -1, 0
	v_writelane_b32 v253, s30, 29
	s_cmp_eq_u32 s3, 2
	s_nop 0
	v_writelane_b32 v253, s31, 30
	s_cselect_b64 s[30:31], -1, 0
	v_writelane_b32 v253, s30, 31
	s_cmp_eq_u32 s3, 1
	s_nop 0
	v_writelane_b32 v253, s31, 32
	s_cselect_b64 s[30:31], -1, 0
	v_writelane_b32 v253, s30, 33
	s_cmp_eq_u32 s3, 0
	s_nop 0
	v_writelane_b32 v253, s31, 34
	s_cselect_b64 s[30:31], -1, 0
	s_lshl_b32 s3, s3, 8
	s_add_u32 s0, s0, s3
	v_writelane_b32 v253, s30, 35
	s_addc_u32 s1, s1, 0
	s_nop 0
	v_writelane_b32 v253, s31, 36
	s_add_u32 s30, s0, 0x1400
	s_addc_u32 s31, s1, 0
	v_writelane_b32 v253, s30, 37
	s_add_u32 s0, s0, 0x2400
	s_addc_u32 s1, s1, 0
	v_writelane_b32 v253, s31, 38
	v_writelane_b32 v253, s0, 39
	s_nop 1
	v_writelane_b32 v253, s1, 40
	s_add_u32 s0, s86, 0xd403400
	s_addc_u32 s1, s87, 0
	v_writelane_b32 v253, s0, 41
	s_nop 1
	v_writelane_b32 v253, s1, 42
	s_add_u32 s0, s86, 0xd403500
	s_addc_u32 s1, s87, 0
	v_writelane_b32 v253, s0, 43
	s_nop 1
	v_writelane_b32 v253, s1, 44
	s_abs_i32 s0, s94
	v_cvt_f32_u32_e32 v0, s0
	s_sub_i32 s1, 0, s0
	v_rcp_iflag_f32_e32 v0, v0
	s_nop 0
	v_mul_f32_e32 v0, 0x4f7ffffe, v0
	v_cvt_u32_f32_e32 v0, v0
	s_nop 0
	v_readfirstlane_b32 s3, v0
	s_mul_i32 s1, s1, s3
	s_mul_hi_u32 s1, s3, s1
	s_add_i32 s3, s3, s1
	s_lshr_b32 s1, s3, 24
	s_mul_i32 s1, s1, s0
	s_sub_i32 s1, 0x100, s1
	s_sub_i32 s3, s1, s0
	s_cmp_ge_u32 s1, s0
	s_cselect_b32 s1, s3, s1
	s_sub_i32 s3, s1, s0
	s_cmp_ge_u32 s1, s0
	s_cselect_b32 s0, s3, s1
	s_lshl_b32 s0, s0, 1
	s_cmp_eq_u32 s0, s94
	s_cselect_b64 s[0:1], -1, 0
	v_writelane_b32 v253, s0, 45
	s_mov_b32 s3, 0x800000
	s_nop 0
	v_writelane_b32 v253, s1, 46
	s_and_b32 s0, s94, 0xffff
	v_cvt_f32_u32_e32 v0, s0
	s_mov_b32 s0, 0x43800000
	v_rcp_iflag_f32_e32 v1, v0
	s_nop 0
	v_mul_f32_e32 v1, 0x43800000, v1
	v_trunc_f32_e32 v1, v1
	v_fma_f32 v2, -v1, v0, s0
	v_cmp_ge_f32_e64 s[0:1], |v2|, v0
	v_cvt_u32_f32_e32 v0, v1
	s_cmp_lg_u64 s[0:1], 0
	s_mul_i32 s0, s95, s94
	s_mul_i32 s15, s0, s2
	v_readfirstlane_b32 s0, v0
	s_addc_u32 s0, s0, 0
	s_and_b32 s0, s0, 0xffff
	v_writelane_b32 v253, s0, 47
	s_lshl_b32 s0, s94, 12
	s_add_i32 s0, s0, 0xfffc0000
	s_ashr_i32 s9, s8, 31
	v_writelane_b32 v253, s0, 48
	v_writelane_b32 v253, s8, 49
	s_ashr_i32 s35, s34, 31
	s_add_i32 s0, s8, 0xffffe080
	v_writelane_b32 v253, s9, 50
	v_writelane_b32 v253, s0, 51
	s_lshl_b64 s[0:1], s[34:35], 11
	v_writelane_b32 v253, s0, 52
	s_lshl_b64 s[98:99], s[34:35], 6
	s_mov_b64 s[8:9], s[4:5]
	v_writelane_b32 v253, s1, 53
	s_lshl_b64 s[0:1], s[34:35], 12
	v_writelane_b32 v253, s0, 54
	v_writelane_b32 v250, s8, 10
	v_mbcnt_lo_u32_b32 v0, -1, 0
	v_writelane_b32 v253, s1, 55
	s_add_u32 s0, s86, 0x4400400
	s_addc_u32 s1, s87, 0
	v_writelane_b32 v253, s0, 56
	v_writelane_b32 v250, s9, 11
	v_mbcnt_hi_u32_b32 v227, -1, v0
	v_writelane_b32 v253, s1, 57
	s_add_u32 s0, s36, 0xc00
	v_writelane_b32 v253, s36, 58
	s_addc_u32 s1, s37, 0
	v_and_b32_e32 v0, 64, v227
	v_writelane_b32 v251, s42, 0
	v_writelane_b32 v251, s43, 1
	v_writelane_b32 v251, s44, 2
	v_writelane_b32 v251, s45, 3
	v_writelane_b32 v251, s46, 4
	v_writelane_b32 v251, s47, 5
	v_writelane_b32 v251, s48, 6
	v_writelane_b32 v251, s49, 7
	v_writelane_b32 v251, s50, 8
	v_writelane_b32 v251, s51, 9
	v_writelane_b32 v251, s0, 10
	v_writelane_b32 v253, s37, 59
	v_writelane_b32 v253, s38, 60
	v_writelane_b32 v251, s1, 11
	v_writelane_b32 v251, s14, 12
	s_lshl_b32 s0, s14, 10
	v_writelane_b32 v251, s0, 13
	s_add_i32 s0, 0, 0x8000
	v_writelane_b32 v251, s0, 14
	s_add_i32 s0, 0, 0xc000
	v_writelane_b32 v251, s0, 15
	s_add_i32 s0, 0, 0x18000
	v_writelane_b32 v251, s0, 16
	s_add_i32 s0, 0, 0x10000
	v_writelane_b32 v251, s0, 17
	s_add_i32 s0, 0, 0x14000
	v_writelane_b32 v251, s0, 18
	s_add_i32 s0, 0, 0x1c000
	v_writelane_b32 v251, s0, 19
	s_add_i32 s0, 0, 0xc00
	v_writelane_b32 v251, s0, 20
	s_add_i32 s0, 0, 0x1400
	v_writelane_b32 v251, s0, 21
	s_add_i32 s0, 0, 0x1800
	v_writelane_b32 v251, s0, 22
	s_add_i32 s0, 0, 0x1c00
	v_writelane_b32 v251, s0, 23
	s_add_i32 s0, 0, 0x2000
	v_writelane_b32 v251, s0, 24
	s_add_i32 s0, 0, 0x2400
	v_writelane_b32 v251, s0, 25
	s_add_i32 s0, 0, 0x2800
	v_writelane_b32 v251, s0, 26
	s_add_i32 s0, 0, 0x2c00
	v_writelane_b32 v251, s0, 27
	s_add_i32 s0, 0, 0x3000
	v_writelane_b32 v251, s0, 28
	s_add_i32 s0, 0, 0x3400
	v_writelane_b32 v251, s0, 29
	s_add_i32 s0, 0, 0x3800
	v_writelane_b32 v251, s0, 30
	s_add_i32 s0, 0, 0x3c00
	v_writelane_b32 v251, s0, 31
	s_add_i32 s0, 0, 0x20400
	v_writelane_b32 v251, s0, 32
	s_add_i32 s0, 0, 0x20020
	v_writelane_b32 v251, s0, 33
	s_add_i32 s0, 0, 0x20024
	v_writelane_b32 v251, s0, 34
	s_mov_b32 s0, s94
	v_writelane_b32 v251, s0, 35
	v_writelane_b32 v253, s39, 61
	s_mov_b64 s[48:49], s[6:7]
	v_writelane_b32 v251, s1, 36
	v_writelane_b32 v251, s84, 37
	v_writelane_b32 v253, s40, 62
	v_writelane_b32 v250, s48, 12
	v_writelane_b32 v251, s85, 38
	v_writelane_b32 v251, s86, 39
	v_writelane_b32 v251, s87, 40
	v_writelane_b32 v251, s82, 41
	v_writelane_b32 v253, s41, 63
	s_mov_b64 s[40:41], s[20:21]
	v_writelane_b32 v251, s83, 42
	v_writelane_b32 v251, s64, 43
	v_writelane_b32 v250, s49, 13
	v_writelane_b32 v250, s40, 14
	v_writelane_b32 v251, s65, 44
	v_writelane_b32 v251, s70, 45
	v_writelane_b32 v251, s66, 46
	s_mov_b64 s[42:43], s[28:29]
	v_writelane_b32 v250, s41, 15
	v_writelane_b32 v251, s67, 47
	v_writelane_b32 v251, s71, 48
	v_writelane_b32 v251, s72, 49
	v_writelane_b32 v251, s10, 50
	v_writelane_b32 v250, s42, 16
	v_add_u32_e32 v228, 64, v0
	v_writelane_b32 v251, s11, 51
	v_writelane_b32 v251, s12, 52
	v_writelane_b32 v250, s43, 17
	v_writelane_b32 v250, s15, 18
	v_writelane_b32 v251, s13, 53
	v_writelane_b32 v251, s16, 54
	v_writelane_b32 v250, s98, 19
	v_xor_b32_e32 v229, 1, v227
	v_writelane_b32 v251, s17, 55
	v_writelane_b32 v251, s18, 56
	v_xor_b32_e32 v230, 2, v227
	v_xor_b32_e32 v231, 4, v227
	v_writelane_b32 v251, s19, 57
	v_writelane_b32 v251, s52, 58
	v_xor_b32_e32 v232, 8, v227
	v_xor_b32_e32 v233, 16, v227
	v_writelane_b32 v251, s53, 59
	v_writelane_b32 v251, s54, 60
	v_xor_b32_e32 v234, 32, v227
	s_lshl_b32 s97, s94, 10
	v_writelane_b32 v251, s55, 61
	s_mov_b32 s35, 0xff800000
	s_mov_b64 s[20:21], 0x800
	v_writelane_b32 v251, s56, 62
	v_writelane_b32 v250, s99, 20
	v_writelane_b32 v250, s97, 21
	v_writelane_b32 v251, s57, 63
	s_branch .LBB0_26

.LBB0_118:
	s_andn2_b64 vcc, exec, s[0:1]
	s_mov_b64 s[0:1], 0
	s_cbranch_vccnz .LBB0_138
	v_readlane_b32 s4, v252, 46
	v_readlane_b32 s5, v252, 47
	s_andn2_b64 vcc, exec, s[4:5]
	s_cbranch_vccnz .LBB0_145
	v_readlane_b32 s14, v252, 57
	v_readlane_b32 s46, v252, 52
	v_readlane_b32 s48, v252, 48
	s_mov_b32 s78, 1
	s_movk_i32 s5, 0x400
	s_mov_b32 s33, 64
	s_movk_i32 s4, 0x800
	v_readlane_b32 s15, v252, 58
	v_readlane_b32 s2, v252, 54
	v_readlane_b32 s47, v252, 53
	v_readlane_b32 s49, v252, 49
	s_branch .LBB0_146

.LBB0_430:
	s_lshl_b32 s8, s29, 8
	s_andn2_b64 vcc, exec, s[0:1]
	s_mov_b32 s29, 0
	s_cbranch_vccnz .LBB0_433
	s_abs_i32 s30, s8
	s_mul_hi_u32 s31, s30, s15
	s_mul_i32 s42, s31, s77
	s_sub_i32 s30, s30, s42
	s_ashr_i32 s29, s8, 31
	s_add_i32 s42, s31, 1
	s_sub_i32 s43, s30, s77
	s_cmp_ge_u32 s30, s77
	s_cselect_b32 s31, s42, s31
	s_cselect_b32 s30, s43, s30
	s_add_i32 s42, s31, 1
	s_cmp_ge_u32 s30, s77
	s_cselect_b32 s30, s42, s31
	s_xor_b32 s30, s30, s29
	s_sub_i32 s29, s30, s29
	s_ashr_i32 s30, s29, 31
	s_mul_i32 s30, s56, s30
	s_mul_hi_u32 s31, s56, s29
	s_add_i32 s30, s31, s30
	s_mul_i32 s31, s57, s29
	s_add_i32 s31, s30, s31
	s_mul_i32 s30, s56, s29
	s_lshl_b64 s[30:31], s[30:31], 1
	s_mov_b64 s[42:43], s[54:55]
	s_add_u32 s30, s42, s30
	s_mul_i32 s42, s29, s77
	s_addc_u32 s31, s43, s31
	s_sub_i32 s8, s8, s42
	v_lshl_add_u32 v132, s28, 8, v246
	v_readlane_b32 s101, v250, 27
	s_nop 3
	s_cmp_eq_u32 s101, 2
	s_cselect_b32 s101, s92, 0
	s_and_b32 s101, s101, 1
	s_lshl_b32 s101, s101, 7
	v_add_u32_e32 v132, s101, v132
	s_and_b64 vcc, exec, s[88:89]
	v_ashrrev_i32_e32 v133, 31, v132
	s_cbranch_vccnz .LBB0_434

.LBB0_433:
	s_mov_b64 s[30:31], s[54:55]
	v_lshl_add_u32 v132, s28, 8, v246
	v_readlane_b32 s101, v250, 27
	s_nop 3
	s_cmp_eq_u32 s101, 2
	s_cselect_b32 s101, s92, 0
	s_and_b32 s101, s101, 1
	s_lshl_b32 s101, s101, 7
	v_add_u32_e32 v132, s101, v132
	s_and_b64 vcc, exec, s[88:89]
	v_ashrrev_i32_e32 v133, 31, v132
	s_cbranch_vccz .LBB0_432

.LBB0_461:
	v_mad_u64_u32 v[102:103], s[30:31], v100, s93, 0
	v_mov_b32_e32 v96, v103
	v_mad_u64_u32 v[100:101], s[30:31], v101, s93, v[96:97]
	v_mov_b32_e32 v103, v100
	v_cvt_pk_bf16_f32 v84, v84, v85
	v_cvt_pk_bf16_f32 v85, v86, v87
	v_cvt_pk_bf16_f32 v86, v80, v81
	v_add_u32_e32 v80, 0x80, v132
	v_lshl_add_u64 v[100:101], v[102:103], 1, v[134:135]
	v_cvt_pk_bf16_f32 v92, v92, v93
	v_cvt_pk_bf16_f32 v93, v94, v95
	v_cvt_pk_bf16_f32 v94, v88, v89
	v_cvt_pk_bf16_f32 v95, v90, v91
	v_cvt_pk_bf16_f32 v87, v82, v83
	s_and_b64 vcc, exec, s[44:45]
	v_ashrrev_i32_e32 v81, 31, v80
	global_store_dwordx4 v[100:101], v[92:95], off sc1
	global_store_dwordx4 v[100:101], v[84:87], off offset:256 sc1
	v_readlane_b32 s101, v250, 27
	s_nop 3
	s_cmp_eq_u32 s101, 2
	s_cbranch_scc1 .Lk1_half_exit
	s_cbranch_vccnz .LBB0_463
	s_waitcnt vmcnt(7)
	v_add_f32_e32 v82, v174, v175
	v_add_f32_e32 v83, v176, v177
	v_add_f32_e32 v82, v82, v83
	v_mov_b32_e32 v83, v82
	s_nop 1
	v_permlane16_swap_b32_e32 v82, v83
	v_add_f32_e32 v82, v82, v83
	v_mov_b32_e32 v83, v82
	s_nop 1
	v_permlane32_swap_b32_e32 v82, v83
	v_add_f32_e32 v82, v82, v83
	v_fmamk_f32 v82, v82, 0x3a800000, v225
	v_rsq_f32_e32 v86, v82
	s_nop 0
	s_branch .LBB0_464

.Lk1_half_exit:
	v_readlane_b32 s98, v250, 19
	v_readlane_b32 s99, v250, 20
	s_branch .LBB0_493
